# ffn_in GEMM tile order variant: per round XCD x takes the 8x8 patch (x>>2, x&3); column tiles fixed per XCD
# baseline (speedup 1.0000x reference)
; __device__ __forceinline__ int tidx() { int t = threadIdx.x; asm volatile("" : "+v"(t)); return t; }
; template <int NT>
; __device__ __forceinline__ void gemm_tile(f32x4 (&acc)[4][NT], const bf16_t* A, int lda, const bf16_t* B, int ldb, int K, bf16_t* sm) {
;     const int tid_ = tidx();
;     bf16_t* sA = sm; bf16_t* sB = sm + 128 * LDT;
;     const int tid = tid_, lane = tid & 63, wid = tid >> 6, wr = wid >> 1, wc = wid & 1;
;     const int fr = lane & 15, fq = lane >> 4;
;     const int lrow = tid >> 3, lkc = tid & 7;
;     const bf16_t* ga = A + (size_t)lrow * lda + lkc * 8;
;     const bf16_t* gb = B + (size_t)lrow * ldb + lkc * 8;
;     int sbrow[NT];
; #pragma unroll
;     for (int i = 0; i < NT; ++i) { const int g = lrow + 32 * i, W_ = 16 * NT, rem = g % W_; sbrow[i] = (g / W_) * W_ + (rem % NT) * 16 + rem / NT; }
; __device__ __forceinline__ void phase_ffn_in(const bf16_t* xb, const bf16_t* W, bf16_t* H, bf16_t* sm) {
;     ...
;     for (int t = blockIdx.x; t < 136 * 32; t += gridDim.x) {
;         const int tm = t >> 5, tn = t & 31;
;         f32x4 acc[4][4]; zero_acc<4>(acc);
;         gemm_tile<4>(acc, xb + (size_t)tm * 128 * 1024, 1024, W + (size_t)tn * 128 * 1024, 1024, 1024, sm);
.LBB0_1479:
	v_mov_b32_e32 v38, v192
	s_bfe_u32 s2, s11, 0x60003
	s_and_b32 s12, s11, 7
	s_cmpk_lt_i32 s11, 0x1000
	s_cbranch_scc0 .Lffn_last
	s_lshr_b32 s18, s11, 9
	s_lshl_b32 s18, s18, 4
	s_lshr_b32 s19, s12, 2
	s_lshl_b32 s19, s19, 3
	s_add_i32 s18, s18, s19
	s_lshr_b32 s19, s2, 3
	s_add_i32 s18, s18, s19
	s_and_b32 s12, s12, 3
	s_lshl_b32 s12, s12, 3
	s_and_b32 s2, s2, 7
	s_add_i32 s12, s12, s2
	s_branch .Lffn_map_done
.Lffn_last:
	s_lshr_b32 s18, s2, 2
	s_addk_i32 s18, 0x80
	s_lshl_b32 s12, s12, 2
	s_and_b32 s2, s2, 3
	s_add_i32 s12, s12, s2
.Lffn_map_done:
	v_ashrrev_i32_e32 v0, 31, v38
	v_ashrrev_i32_e32 v30, 3, v38
	v_lshrrev_b32_e32 v0, 26, v0
	v_add_u32_e32 v0, v30, v0
	v_lshrrev_b32_e32 v1, 6, v0
	v_mul_i32_i24_e32 v1, 64, v1
	v_sub_u32_e32 v1, v30, v1
	v_lshrrev_b16_sdwa v2, v196, sext(v1) dst_sel:DWORD dst_unused:UNUSED_PAD src0_sel:DWORD src1_sel:BYTE_0
	v_and_b32_e32 v2, 3, v2
	v_add_u16_e32 v2, v1, v2
	v_ashrrev_i16_sdwa v3, v197, sext(v2) dst_sel:DWORD dst_unused:UNUSED_PAD src0_sel:DWORD src1_sel:BYTE_0
	v_and_b32_e32 v2, 0xfc, v2
	v_sub_u16_e32 v1, v1, v2
	v_and_b32_e32 v0, 0x7ffffc0, v0
	v_lshlrev_b32_sdwa v1, v198, sext(v1) dst_sel:DWORD dst_unused:UNUSED_PAD src0_sel:DWORD src1_sel:BYTE_0
	v_bfe_i32 v2, v3, 0, 16
	v_add3_u32 v39, v0, v2, v1
	v_add_u32_e32 v0, 32, v30
	v_ashrrev_i32_e32 v1, 31, v0
	v_lshrrev_b32_e32 v1, 26, v1
	v_add_u32_e32 v1, v0, v1
	v_lshrrev_b32_e32 v2, 6, v1
	v_mul_i32_i24_e32 v2, 64, v2
	v_sub_u32_e32 v0, v0, v2
	v_lshrrev_b16_sdwa v2, v196, sext(v0) dst_sel:DWORD dst_unused:UNUSED_PAD src0_sel:DWORD src1_sel:BYTE_0
	v_and_b32_e32 v2, 3, v2
	v_add_u16_e32 v2, v0, v2
	v_ashrrev_i16_sdwa v3, v197, sext(v2) dst_sel:DWORD dst_unused:UNUSED_PAD src0_sel:DWORD src1_sel:BYTE_0
	v_and_b32_e32 v2, 0xfc, v2
	v_sub_u16_e32 v0, v0, v2
	v_and_b32_e32 v1, 0x7ffffc0, v1
	v_lshlrev_b32_sdwa v0, v198, sext(v0) dst_sel:DWORD dst_unused:UNUSED_PAD src0_sel:DWORD src1_sel:BYTE_0
	v_bfe_i32 v2, v3, 0, 16
	v_add3_u32 v40, v1, v2, v0
	v_add_u32_e32 v0, 64, v30
	v_ashrrev_i32_e32 v1, 31, v0
	v_lshrrev_b32_e32 v1, 26, v1
	v_add_u32_e32 v1, v0, v1
	v_lshrrev_b32_e32 v2, 6, v1
	v_mul_i32_i24_e32 v2, 64, v2
	v_sub_u32_e32 v0, v0, v2
	v_lshrrev_b16_sdwa v2, v196, sext(v0) dst_sel:DWORD dst_unused:UNUSED_PAD src0_sel:DWORD src1_sel:BYTE_0
	v_and_b32_e32 v2, 3, v2
	v_add_u16_e32 v2, v0, v2
	v_ashrrev_i16_sdwa v3, v197, sext(v2) dst_sel:DWORD dst_unused:UNUSED_PAD src0_sel:DWORD src1_sel:BYTE_0
	v_and_b32_e32 v2, 0xfc, v2
	v_sub_u16_e32 v0, v0, v2
	v_and_b32_e32 v1, 0x7ffffc0, v1
	v_lshlrev_b32_sdwa v0, v198, sext(v0) dst_sel:DWORD dst_unused:UNUSED_PAD src0_sel:DWORD src1_sel:BYTE_0
	v_bfe_i32 v2, v3, 0, 16
	s_waitcnt lgkmcnt(0)
	v_add3_u32 v41, v1, v2, v0
	v_add_u32_e32 v0, 0x60, v30
	v_ashrrev_i32_e32 v1, 31, v0
	v_lshrrev_b32_e32 v1, 26, v1
	v_add_u32_e32 v1, v0, v1
	v_lshrrev_b32_e32 v2, 6, v1
	v_mul_i32_i24_e32 v2, 64, v2
	v_sub_u32_e32 v0, v0, v2
	v_lshrrev_b16_sdwa v2, v196, sext(v0) dst_sel:DWORD dst_unused:UNUSED_PAD src0_sel:DWORD src1_sel:BYTE_0
	s_mov_b32 s2, s12
	s_ashr_i32 s19, s18, 31
	v_and_b32_e32 v2, 3, v2
	s_lshl_b32 s86, s2, 18
	s_lshl_b64 s[22:23], s[18:19], 18
	v_add_u16_e32 v2, v0, v2
	s_add_u32 s24, s80, s22
	v_ashrrev_i16_sdwa v3, v197, sext(v2) dst_sel:DWORD dst_unused:UNUSED_PAD src0_sel:DWORD src1_sel:BYTE_0
	v_and_b32_e32 v2, 0xfc, v2
	s_addc_u32 s25, s81, s23
	s_lshl_b32 s2, s12, 18
	v_sub_u16_e32 v0, v0, v2
	s_add_u32 s40, s16, s2
	v_and_b32_e32 v1, 0x7ffffc0, v1
	v_lshlrev_b32_sdwa v0, v198, sext(v0) dst_sel:DWORD dst_unused:UNUSED_PAD src0_sel:DWORD src1_sel:BYTE_0
	v_bfe_i32 v2, v3, 0, 16
	v_ashrrev_i32_e32 v31, 31, v30
	s_addc_u32 s41, s17, 0
	v_add3_u32 v42, v1, v2, v0
	v_lshlrev_b64 v[32:33], 11, v[30:31]
	v_lshlrev_b32_e32 v2, 4, v38
	v_lshl_add_u64 v[0:1], s[40:41], 0, v[32:33]
	v_and_b32_e32 v12, 0x70, v2
	v_lshl_add_u64 v[8:9], v[0:1], 0, v[12:13]
	v_add_co_u32_e32 v0, vcc, s7, v8
	v_lshl_add_u64 v[18:19], s[24:25], 0, v[32:33]
	s_nop 0
	v_addc_co_u32_e32 v1, vcc, 0, v9, vcc
	v_add_co_u32_e32 v10, vcc, s37, v8
	v_lshl_add_u64 v[26:27], v[18:19], 0, v[12:13]
	s_nop 0
	v_addc_co_u32_e32 v11, vcc, 0, v9, vcc
	v_add_co_u32_e32 v14, vcc, s73, v8
	v_mov_b32_e32 v250, v8
	v_mov_b32_e32 v251, v9
	s_nop 0
	v_addc_co_u32_e32 v15, vcc, 0, v9, vcc
	v_add_co_u32_e32 v18, vcc, s7, v26
	s_nop 0
	v_addc_co_u32_e32 v19, vcc, 0, v27, vcc
	v_add_co_u32_e32 v28, vcc, s37, v26
	v_mov_b32_e32 v248, v26
	v_mov_b32_e32 v249, v27
	s_nop 0
	v_addc_co_u32_e32 v29, vcc, 0, v27, vcc
	v_add_co_u32_e32 v34, vcc, s73, v26
	v_and_b32_e32 v31, 15, v38
	s_nop 0
	v_addc_co_u32_e32 v35, vcc, 0, v27, vcc
	s_nop 0
	v_lshrrev_b32_e32 v44, 1, v38
	v_and_or_b32 v31, v44, s3, v31
	v_mul_lo_u32 v44, v31, s89
	v_mul_lo_u32 v45, v30, s89
	v_lshl_add_u64 v[30:31], s[22:23], 0, v[32:33]
	v_or_b32_e32 v30, v30, v12
	v_lshl_add_u64 v[98:99], s[58:59], 0, v[30:31]
	v_lshl_add_u64 v[30:31], s[86:87], 0, v[32:33]
	v_and_b32_e32 v43, 48, v38
	v_and_b32_e32 v38, 0x4f, v38
	v_or_b32_e32 v30, v30, v12
	v_mul_u32_u24_e32 v38, 0xa0, v38
	v_mul_lo_u32 v39, v39, s89
	v_mul_lo_u32 v40, v40, s89
	v_mul_lo_u32 v41, v41, s89
	v_mul_lo_u32 v42, v42, s89
; template <int NT>
; __device__ __forceinline__ void gemm_tile(f32x4 (&acc)[4][NT], const bf16_t* A, int lda, const bf16_t* B, int ldb, int K, bf16_t* sm) {
;     ...
;     const bf16_t* ga = A + (size_t)lrow * lda + lkc * 8;
;     const bf16_t* gb = B + (size_t)lrow * ldb + lkc * 8;
;     int sbrow[NT];
; #pragma unroll
;     for (int i = 0; i < NT; ++i) { const int g = lrow + 32 * i, W_ = 16 * NT, rem = g % W_; sbrow[i] = (g / W_) * W_ + (rem % NT) * 16 + rem / NT; }
;     u32x4 ra0[4], rb0[NT];
; #pragma unroll
;     for (int i = 0; i < 4; ++i) ra0[i] = *(const u32x4*)(ga + (size_t)(32 * i) * lda);
; #pragma unroll
;     for (int i = 0; i < NT; ++i) rb0[i] = *(const u32x4*)(gb + (size_t)(32 * i) * ldb);
;     const int nk = K >> 6;
;     for (int kt = 0; kt < nk; ++kt) {
;         lds_barrier();
; #pragma unroll
;         for (int i = 0; i < 4; ++i) *(u32x4*)(sA + (lrow + 32 * i) * LDT + lkc * 8) = ra0[i];
; #pragma unroll
;         for (int i = 0; i < NT; ++i) *(u32x4*)(sB + sbrow[i] * LDT + lkc * 8) = rb0[i];
;         lds_barrier();
;         if (kt + 1 < nk) {
;             ga += 64; gb += 64;
; #pragma unroll
;             for (int i = 0; i < 4; ++i) ra0[i] = *(const u32x4*)(ga + (size_t)(32 * i) * lda);
; #pragma unroll
;             for (int i = 0; i < NT; ++i) rb0[i] = *(const u32x4*)(gb + (size_t)(32 * i) * ldb);
;         }
	v_lshl_add_u64 v[100:101], s[16:17], 0, v[30:31]
	v_mov_b32_e32 v30, 0
	s_mov_b64 s[22:23], 0
	v_add_u32_e32 v105, v12, v45
	v_add_u32_e32 v106, v12, v39
	v_add_u32_e32 v107, v12, v40
	v_add_u32_e32 v108, v12, v41
	v_add_u32_e32 v109, v12, v42
	v_add_u32_e32 v104, v43, v44
	v_add_u32_e32 v12, v43, v38
	v_mov_b32_e32 v31, v30
	v_mov_b32_e32 v32, v30
	v_mov_b32_e32 v33, v30
	v_mov_b32_e32 v38, v30
	v_mov_b32_e32 v39, v30
	v_mov_b32_e32 v40, v30
	v_mov_b32_e32 v41, v30
	v_mov_b32_e32 v42, v30
	v_mov_b32_e32 v43, v30
	v_mov_b32_e32 v44, v30
	v_mov_b32_e32 v45, v30
	v_mov_b32_e32 v46, v30
	v_mov_b32_e32 v47, v30
	v_mov_b32_e32 v48, v30
	v_mov_b32_e32 v49, v30
	v_mov_b32_e32 v50, v30
	v_mov_b32_e32 v51, v30
	v_mov_b32_e32 v52, v30
	v_mov_b32_e32 v53, v30
	v_mov_b32_e32 v54, v30
	v_mov_b32_e32 v55, v30
	v_mov_b32_e32 v56, v30
	v_mov_b32_e32 v57, v30
	v_mov_b32_e32 v58, v30
	v_mov_b32_e32 v59, v30
	v_mov_b32_e32 v60, v30
	v_mov_b32_e32 v61, v30
	v_mov_b32_e32 v62, v30
	v_mov_b32_e32 v63, v30
	v_mov_b32_e32 v64, v30
	v_mov_b32_e32 v65, v30
	v_mov_b32_e32 v66, v30
	v_mov_b32_e32 v67, v30
	v_mov_b32_e32 v68, v30
	v_mov_b32_e32 v69, v30
	v_mov_b32_e32 v70, v30
	v_mov_b32_e32 v71, v30
	v_mov_b32_e32 v72, v30
	v_mov_b32_e32 v73, v30
	v_mov_b32_e32 v74, v30
	v_mov_b32_e32 v75, v30
	v_mov_b32_e32 v76, v30
	v_mov_b32_e32 v77, v30
	v_mov_b32_e32 v78, v30
	v_mov_b32_e32 v79, v30
	v_mov_b32_e32 v80, v30
	v_mov_b32_e32 v81, v30
	v_mov_b32_e32 v82, v30
	v_mov_b32_e32 v83, v30
	v_mov_b32_e32 v84, v30
	v_mov_b32_e32 v85, v30
	v_mov_b32_e32 v86, v30
	v_mov_b32_e32 v87, v30
	v_mov_b32_e32 v88, v30
	v_mov_b32_e32 v89, v30
	v_mov_b32_e32 v90, v30
	v_mov_b32_e32 v91, v30
	v_mov_b32_e32 v92, v30
	v_mov_b32_e32 v93, v30
	v_mov_b32_e32 v94, v30
	v_mov_b32_e32 v95, v30
	v_mov_b32_e32 v96, v30
	v_mov_b32_e32 v97, v30
	v_writelane_b32 v234, s90, 0
	v_writelane_b32 v234, s91, 1
	v_writelane_b32 v234, s92, 2
	v_writelane_b32 v234, s93, 3
	v_writelane_b32 v234, s94, 4
	v_writelane_b32 v234, s95, 5
	v_bfe_u32 v160, v192, 3, 3
	v_and_b32_e32 v161, 7, v192
	v_xor_b32_e32 v161, v160, v161
	v_lshlrev_b32_e32 v161, 4, v161
	v_lshrrev_b32_e32 v162, 6, v192
	v_lshl_add_u32 v163, v162, 5, v160
	v_mul_u32_u24_e32 v163, 0x800, v163
	v_add_u32_e32 v236, v163, v161
	v_add_u32_e32 v237, 0x3c00, v236
	v_add_u32_e32 v238, 0x3c00, v237
	v_add_u32_e32 v239, 0x3c00, v238
	v_lshrrev_b32_e32 v163, 7, v192
	v_bfe_u32 v162, v192, 6, 1
	v_lshlrev_b32_e32 v163, 6, v163
	v_lshl_add_u32 v163, v160, 2, v163
	v_lshl_add_u32 v163, v162, 1, v163
	v_mul_u32_u24_e32 v163, 0x800, v163
	v_add_u32_e32 v240, v163, v161
	v_add_u32_e32 v241, 0xfc00, v240
	v_subrev_u32_e32 v242, 0xfc00, v241
	v_add_u32_e32 v243, 0xfc00, v242
	v_and_b32_e32 v160, 15, v192
	v_bfe_u32 v161, v192, 4, 2
	v_and_b32_e32 v162, 7, v160
	v_xor_b32_e32 v161, v161, v162
	v_lshlrev_b32_e32 v161, 4, v161
	v_lshl_add_u32 v161, v160, 7, v161
	v_lshrrev_b32_e32 v162, 7, v192
	v_lshl_add_u32 v244, v162, 13, v161
	v_bfe_u32 v162, v192, 6, 1
	v_lshl_add_u32 v246, v162, 13, v161
	v_add_u32_e32 v246, 0x4000, v246
	v_xor_b32_e32 v245, 64, v244
	v_xor_b32_e32 v247, 64, v246
	v_lshrrev_b32_e32 v160, 6, v192
	s_nop 0
	v_readfirstlane_b32 s94, v160
	v_readfirstlane_b32 s90, v248
	v_readfirstlane_b32 s91, v249
	v_readfirstlane_b32 s92, v250
	v_readfirstlane_b32 s93, v251
	s_mul_i32 s95, s94, 0x4000
	s_sub_u32 s90, s90, s95
	s_subb_u32 s91, s91, 0
	s_mul_i32 s95, s94, 0x4000
	s_sub_u32 s92, s92, s95
	s_subb_u32 s93, s93, 0
	s_lshl_b32 s94, s94, 10
	s_waitcnt lgkmcnt(0)
	s_barrier
	s_lshl_b32 s95, s94, 2
	s_add_u32 m0, s95, 0x0
	s_nop 0
	global_load_lds_dwordx4 v236, s[90:91]
	global_load_lds_dwordx4 v237, s[90:91] offset:1024
	global_load_lds_dwordx4 v238, s[90:91] offset:2048
	global_load_lds_dwordx4 v239, s[90:91] offset:3072
	s_mul_i32 s95, s94, 4
	s_add_u32 m0, s95, 0x4000
	s_nop 0
	global_load_lds_dwordx4 v240, s[92:93]
	global_load_lds_dwordx4 v241, s[92:93] offset:1024
	global_load_lds_dwordx4 v242, s[92:93] offset:2048
	global_load_lds_dwordx4 v243, s[92:93] offset:3072
	s_add_u32 s90, s90, 0x80
	s_addc_u32 s91, s91, 0
	s_add_u32 s92, s92, 0x80
	s_addc_u32 s93, s93, 0
	s_waitcnt vmcnt(0)
	s_barrier
	s_lshl_b32 s95, s94, 2
	s_add_u32 m0, s95, 0x8000
	s_nop 0
	global_load_lds_dwordx4 v236, s[90:91]
	global_load_lds_dwordx4 v237, s[90:91] offset:1024
	global_load_lds_dwordx4 v238, s[90:91] offset:2048
	global_load_lds_dwordx4 v239, s[90:91] offset:3072
	s_mul_i32 s95, s94, 4
	s_add_u32 m0, s95, 0xc000
	s_nop 0
	global_load_lds_dwordx4 v240, s[92:93]
	global_load_lds_dwordx4 v241, s[92:93] offset:1024
	global_load_lds_dwordx4 v242, s[92:93] offset:2048
	global_load_lds_dwordx4 v243, s[92:93] offset:3072
	s_add_u32 s90, s90, 0x80
	s_addc_u32 s91, s91, 0
	s_add_u32 s92, s92, 0x80
	s_addc_u32 s93, s93, 0
	ds_read_b128 v[110:113], v244 offset:0
	ds_read_b128 v[114:117], v244 offset:2048
	ds_read_b128 v[118:121], v244 offset:4096
	ds_read_b128 v[122:125], v244 offset:6144
	ds_read_b128 v[126:129], v246 offset:0
	ds_read_b128 v[130:133], v246 offset:2048
	ds_read_b128 v[134:137], v246 offset:4096
	ds_read_b128 v[138:141], v246 offset:6144
	s_movk_i32 s95, 0x6
	s_cmp_eq_u32 s95, 0
	s_cbranch_scc1 .Lgemm_x1480
